# forgetting-mixer tile loop (wave 0): log-forget suffix sum via DPP row shifts + readlanes instead of 7 dependent ds_bpermute round trips per tile; stacked on the epilogue de-serialisation version
# speedup vs baseline: 1.0103x; 1.0005x over previous
.LBB0_354:
	v_mov_b32_e32 v0, s23
	ds_read_b32 v122, v0
	s_waitcnt lgkmcnt(0)
	v_pk_add_f32 v[34:35], v[198:199], v[122:123]
	s_nop 0
	v_cmp_gt_f32_e32 vcc, v34, v35
	s_cmp_lg_u64 vcc, 0
	s_cselect_b64 s[14:15], -1, 0
	s_and_saveexec_b64 s[16:17], s[40:41]
	v_cndmask_b32_e64 v0, 0, 1, s[14:15]
	v_mov_b32_e32 v34, s29
	ds_write_b32 v34, v0
	s_or_b64 exec, exec, s[16:17]
	s_add_i32 s72, s68, -1
	s_cmp_lt_u32 s72, s85
	s_cselect_b64 s[18:19], -1, 0
	s_cmp_ge_u32 s72, s85
	s_cbranch_scc1 .LBB0_359
	v_add_u32_e32 v0, 0xaa00, v135
	s_and_b64 vcc, exec, s[36:37]
	s_waitcnt vmcnt(1)
	ds_write_b128 v134, v[90:93] offset:9216
	s_waitcnt vmcnt(0)
	ds_write2_b64 v0, v[94:95], v[96:97] offset1:1
	s_cbranch_vccnz .LBB0_359
	v_mov_b32_e32 v0, v141
	v_mbcnt_lo_u32_b32 v36, -1, 0
	v_mbcnt_hi_u32_b32 v36, -1, v36
	v_add_f32_dpp v0, v0, v0 row_shl:1 row_mask:0xf bank_mask:0xf bound_ctrl:0
	s_nop 1
	v_add_f32_dpp v0, v0, v0 row_shl:2 row_mask:0xf bank_mask:0xf bound_ctrl:0
	s_nop 1
	v_add_f32_dpp v0, v0, v0 row_shl:4 row_mask:0xf bank_mask:0xf bound_ctrl:0
	s_nop 1
	v_add_f32_dpp v0, v0, v0 row_shl:8 row_mask:0xf bank_mask:0xf bound_ctrl:0
	v_cmp_gt_u32_e32 vcc, 16, v36
	s_nop 0
	v_readlane_b32 s99, v0, 48
	v_readlane_b32 s100, v0, 32
	v_readlane_b32 s101, v0, 16
	v_mov_b32_e32 v34, 0
	s_nop 0
	v_mov_b32_e32 v35, s99
	v_cndmask_b32_e64 v34, v34, v35, s[50:51]
	v_add_f32_e32 v35, s100, v34
	v_cndmask_b32_e64 v34, v34, v35, s[38:39]
	v_add_f32_e32 v35, s101, v34
	v_cndmask_b32_e32 v34, v34, v35, vcc
	v_add_f32_e32 v0, v0, v34
	s_nop 0
	v_readlane_b32 s99, v0, 0
	v_add_f32_e32 v0, v137, v0
	v_sub_f32_e32 v0, v0, v141
	v_mul_f32_e32 v0, 0x3fb8aa3b, v0
	ds_write_b32 v147, v0 offset:256
	v_add_f32_e32 v137, s99, v137

.LBB0_380:
	v_mov_b32_e32 v0, s60
	ds_read_b32 v120, v0
	s_waitcnt lgkmcnt(0)
	v_pk_add_f32 v[34:35], v[198:199], v[120:121]
	s_nop 0
	v_cmp_gt_f32_e32 vcc, v34, v35
	s_cmp_lg_u64 vcc, 0
	s_cselect_b64 s[14:15], -1, 0
	s_and_saveexec_b64 s[16:17], s[40:41]
	v_cndmask_b32_e64 v0, 0, 1, s[14:15]
	v_mov_b32_e32 v34, s29
	ds_write_b32 v34, v0 offset:32
	s_or_b64 exec, exec, s[16:17]
	s_andn2_b64 vcc, exec, s[10:11]
	s_cbranch_vccnz .LBB0_385
	s_and_b64 vcc, exec, s[36:37]
	s_waitcnt vmcnt(1)
	ds_write_b128 v134, v[82:85]
	s_waitcnt vmcnt(0)
	ds_write2_b64 v136, v[86:87], v[88:89] offset1:1
	s_cbranch_vccnz .LBB0_385
	v_mov_b32_e32 v0, v133
	v_mbcnt_lo_u32_b32 v36, -1, 0
	v_mbcnt_hi_u32_b32 v36, -1, v36
	v_add_f32_dpp v0, v0, v0 row_shl:1 row_mask:0xf bank_mask:0xf bound_ctrl:0
	s_nop 1
	v_add_f32_dpp v0, v0, v0 row_shl:2 row_mask:0xf bank_mask:0xf bound_ctrl:0
	s_nop 1
	v_add_f32_dpp v0, v0, v0 row_shl:4 row_mask:0xf bank_mask:0xf bound_ctrl:0
	s_nop 1
	v_add_f32_dpp v0, v0, v0 row_shl:8 row_mask:0xf bank_mask:0xf bound_ctrl:0
	v_cmp_gt_u32_e32 vcc, 16, v36
	s_nop 0
	v_readlane_b32 s99, v0, 48
	v_readlane_b32 s100, v0, 32
	v_readlane_b32 s101, v0, 16
	v_mov_b32_e32 v34, 0
	s_nop 0
	v_mov_b32_e32 v35, s99
	v_cndmask_b32_e64 v34, v34, v35, s[50:51]
	v_add_f32_e32 v35, s100, v34
	v_cndmask_b32_e64 v34, v34, v35, s[38:39]
	v_add_f32_e32 v35, s101, v34
	v_cndmask_b32_e32 v34, v34, v35, vcc
	v_add_f32_e32 v0, v0, v34
	s_nop 0
	v_readlane_b32 s99, v0, 0
	v_add_f32_e32 v0, v137, v0
	v_sub_f32_e32 v0, v0, v133
	v_mul_f32_e32 v0, 0x3fb8aa3b, v0
	ds_write_b32 v147, v0
	v_add_f32_e32 v137, s99, v137
